# GEMM1 units after a workgroup's first one drawn from a per-XCD ticket counter (workgroup-uniform: wave 0 draws one unit ahead and publishes through an LDS word behind a K-loop barrier), same template
# speedup vs baseline: 1.0015x; 1.0015x over previous
.LBB0_117:
	s_and_b64 vcc, exec, s[10:11]
	s_cbranch_vccz .LBB0_196
	s_cmpk_gt_i32 s2, 0x9ff
	v_readfirstlane_b32 s1, v0
	s_cbranch_scc1 .LBB0_134
	s_and_b32 s98, s2, 7
	s_lshl_b32 s98, s98, 8
	s_add_u32 s98, s98, 0x90000
	s_add_u32 s98, s34, s98
	s_addc_u32 s99, s35, 0
	v_mov_b32_e32 v253, 0
	v_mov_b32_e32 v254, 1
	v_mov_b32_e32 v255, 0x20440
	s_cmp_lg_u32 s33, 0
	s_cbranch_scc1 .Lp1d_noatom0
	s_mov_b64 s[96:97], exec
	s_mov_b64 exec, 1
	global_atomic_add v252, v253, v254, s[98:99] sc0
	s_mov_b64 exec, s[96:97]
.Lp1d_noatom0:
	v_lshrrev_b32_e32 v1, 5, v0
	s_waitcnt vmcnt(8)
	v_lshrrev_b32_e32 v3, 1, v0
	v_and_b32_e32 v1, 4, v1
	v_bfe_u32 v2, v0, 2, 2
	v_and_b32_e32 v14, 24, v3
	v_or3_b32 v1, v1, v2, v14
	v_lshlrev_b32_e32 v2, 4, v0
	v_or_b32_e32 v10, 0x2000, v2
	v_lshrrev_b32_e32 v3, 7, v10
	s_movk_i32 s0, 0x60
	v_and_or_b32 v4, v3, s0, v1
	v_bfe_u32 v13, v0, 2, 4
	s_movk_i32 s0, 0x70
	s_waitcnt lgkmcnt(0)
	s_ashr_i32 s45, s2, 31
	v_and_or_b32 v3, v3, s0, v13
	s_lshr_b32 s0, s45, 29
	s_add_i32 s0, s2, s0
	s_lshr_b32 s8, s1, 6
	s_ashr_i32 s6, s0, 3
	s_and_b32 s0, s0, -8
	s_lshr_b32 s10, s1, 8
	s_lshl_b32 s44, s8, 10
	s_sub_i32 s0, s2, s0
	s_cmp_lt_i32 s0, 0
	s_movk_i32 s46, 0x141
	s_cselect_b32 s7, s46, 0x140
	s_mul_i32 s0, s0, s7
	s_add_i32 s0, s0, s6
	s_mul_hi_i32 s6, s0, 0x66666667
	s_lshr_b32 s7, s6, 31
	s_ashr_i32 s6, s6, 5
	s_add_i32 s6, s6, s7
	s_lshl_b32 s7, s6, 3
	s_mulk_i32 s6, 0x50
	s_sub_i32 s6, s0, s6
	s_bfe_i32 s0, s6, 0x80000
	s_bfe_u32 s0, s0, 0x3000c
	s_add_i32 s9, s6, s0
	s_bfe_i32 s0, s9, 0x80000
	s_and_b32 s9, s9, 0xf8
	s_sub_i32 s6, s6, s9
	s_sext_i32_i16 s0, s0
	s_sext_i32_i8 s6, s6
	v_and_b32_e32 v5, 32, v0
	s_lshr_b32 s0, s0, 3
	s_add_i32 s36, s7, s6
	v_bitop3_b32 v11, v2, v5, 48 bitop3:0x6c
	v_and_b32_e32 v12, 64, v0
	s_ashr_i32 s37, s36, 31
	s_bfe_i64 s[12:13], s[0:1], 0x100000
	v_or_b32_e32 v2, v11, v12
	s_lshl_b64 s[6:7], s[36:37], 19
	s_lshl_b64 s[12:13], s[12:13], 19
	v_lshl_or_b32 v132, v3, 11, v2
	v_lshrrev_b32_e32 v3, 3, v0
	s_add_u32 s40, s72, s12
	v_and_or_b32 v1, v3, 32, v1
	s_addc_u32 s41, s73, s13
	s_add_i32 s47, s44, 0
	v_lshl_or_b32 v134, v1, 11, v2
	s_add_i32 m0, s47, 0x10000
	v_lshl_or_b32 v130, v4, 11, v2
	global_load_lds_dwordx4 v134, s[40:41]
	s_add_i32 m0, s47, 0x12000
	s_add_u32 s12, s40, 0x40000
	global_load_lds_dwordx4 v130, s[40:41]
	s_addc_u32 s13, s41, 0
	s_add_i32 m0, s47, 0x14000
	v_and_or_b32 v1, v3, 48, v13
	global_load_lds_dwordx4 v134, s[12:13]
	s_add_i32 m0, s47, 0x16000
	s_add_u32 s38, s16, s6
	s_addc_u32 s39, s17, s7
	s_add_i32 s50, s47, 0x2000
	v_lshl_or_b32 v136, v1, 11, v2
	global_load_lds_dwordx4 v130, s[12:13]
	s_mov_b32 m0, s47
	s_add_u32 s6, s38, 0x40000
	global_load_lds_dwordx4 v136, s[38:39]
	s_mov_b32 m0, s50
	s_addc_u32 s7, s39, 0
	s_add_i32 s51, s47, 0x4000
	global_load_lds_dwordx4 v132, s[38:39]
	s_mov_b32 m0, s51
	s_add_i32 s52, s47, 0x6000
	global_load_lds_dwordx4 v136, s[6:7]
	s_mov_b32 m0, s52
	v_mov_b32_e32 v135, 0
	global_load_lds_dwordx4 v132, s[6:7]
	v_mov_b32_e32 v131, v135
	v_mov_b32_e32 v137, v135
	v_mov_b32_e32 v133, v135
	s_cmp_eq_u32 s10, 1
	s_mov_b32 s53, 0
	v_lshl_add_u64 v[8:9], s[40:41], 0, v[134:135]
	v_lshl_add_u64 v[6:7], s[40:41], 0, v[130:131]
	v_lshl_add_u64 v[2:3], s[38:39], 0, v[136:137]
	s_cselect_b64 s[6:7], -1, 0
	s_cmp_lg_u32 s10, 1
	v_lshl_add_u64 v[4:5], s[38:39], 0, v[132:133]
	s_cbranch_scc1 .LBB0_121
	s_barrier
.LBB0_121:
	s_lshl_b32 s14, s8, 5
	s_mov_b64 s[8:9], 0x80
	s_and_b32 s79, s14, 0x60
	s_add_i32 m0, s47, 0x18000
	v_lshl_add_u64 v[8:9], v[8:9], 0, s[8:9]
	s_lshl_b32 s11, s10, 13
	s_lshl_b32 s15, s79, 7
	s_waitcnt vmcnt(2)
	s_cmp_lg_u32 s33, 0
	s_cbranch_scc1 .Lp1d_nopub0
	v_readfirstlane_b32 s96, v252
	s_nop 3
	v_mov_b32_e32 v251, s96
	ds_write_b32 v255, v251
	s_waitcnt lgkmcnt(0)
.Lp1d_nopub0:
	s_barrier
	global_load_lds_dwordx4 v[8:9], off
	v_lshl_add_u64 v[6:7], v[6:7], 0, s[8:9]
	s_add_i32 m0, s47, 0x1a000
	s_add_i32 s80, s47, 0x8000
	s_add_i32 s81, s47, 0xa000
	global_load_lds_dwordx4 v[6:7], off
	v_lshl_add_u64 v[2:3], v[2:3], 0, s[8:9]
	s_mov_b32 m0, s80
	s_add_u32 s12, s40, 0x40080
	global_load_lds_dwordx4 v[2:3], off
	v_lshl_add_u64 v[2:3], v[4:5], 0, s[8:9]
	s_mov_b32 m0, s81
	s_addc_u32 s13, s41, 0
	global_load_lds_dwordx4 v[2:3], off
	s_add_i32 m0, s47, 0x1c000
	v_lshl_add_u64 v[2:3], s[12:13], 0, v[134:135]
	global_load_lds_dwordx4 v[2:3], off
	v_lshl_add_u64 v[2:3], s[12:13], 0, v[130:131]
	s_add_i32 m0, s47, 0x1e000
	v_lshlrev_b32_e32 v4, 2, v0
	global_load_lds_dwordx4 v[2:3], off
	v_and_b32_e32 v2, 15, v0
	v_lshlrev_b32_e32 v3, 1, v14
	v_lshl_or_b32 v1, s10, 6, v2
	v_lshl_or_b32 v2, v2, 6, v3
	v_and_b32_e32 v4, 32, v4
	s_sext_i32_i8 s37, s0
	v_bitop3_b32 v5, v2, s11, v4 bitop3:0xde
	v_lshlrev_b32_e32 v2, 6, v0
	s_movk_i32 s0, 0x3c0
	v_and_or_b32 v2, v2, s0, v3
	v_bitop3_b32 v150, s15, v2, v4 bitop3:0xf6
	v_and_or_b32 v2, s14, 32, v14
	v_lshlrev_b32_e32 v2, 1, v2
	v_mov_b32_e32 v3, v135
	v_lshl_add_u64 v[138:139], s[20:21], 0, v[2:3]
	v_lshlrev_b32_e32 v2, 8, v0
	v_and_b32_e32 v2, 0x18000, v2
	v_lshlrev_b32_e32 v3, 11, v13
	v_or3_b32 v2, v11, v2, v3
	v_add_u32_e32 v140, v2, v12
	v_lshlrev_b32_e32 v2, 4, v10
	s_waitcnt vmcnt(6)
	s_cmpk_lt_u32 s1, 0x100
	v_and_b32_e32 v2, 0x38000, v2
	s_cselect_b64 s[10:11], -1, 0
	v_or3_b32 v2, v11, v2, v3
	s_add_i32 s83, 0, 0x10000
	s_add_i32 s84, 0, 0x14000
	s_ashr_i32 s82, s3, 31
	v_mov_b32_e32 v141, v135
	v_add_u32_e32 v142, v2, v12
	v_mov_b32_e32 v143, v135
	v_mov_b64_e32 v[144:145], 0xa00
	v_mov_b64_e32 v[146:147], 0x9ff
	v_add_u32_e32 v151, s83, v150
	v_add_u32_e32 v152, s84, v150
	v_add_u32_e32 v153, 0, v5
	s_mov_b64 s[12:13], 0x4000
	s_mov_b64 s[14:15], 0x4800
	s_mov_b64 s[18:19], 0x5000
	s_mov_b64 s[22:23], 0x5800
	s_barrier
	s_branch .LBB0_124

.LBB0_124:
	s_add_i32 s53, s53, 1
	ds_read_b32 v251, v255
	s_waitcnt lgkmcnt(0)
	v_readfirstlane_b32 s28, v251
	s_nop 3
	s_add_i32 s28, s28, 32
	s_lshl_b32 s28, s28, 3
	s_and_b32 s29, s2, 7
	s_or_b32 s28, s28, s29
	s_mov_b32 s29, 0
	s_cmp_lg_u32 s33, 0
	s_cbranch_scc1 .Lp1d_noatom
	s_mov_b64 s[96:97], exec
	s_mov_b64 exec, 1
	global_atomic_add v252, v253, v254, s[98:99] sc0
	s_mov_b64 exec, s[96:97]
.Lp1d_noatom:
	v_cmp_gt_i64_e32 vcc, s[28:29], v[146:147]
	v_cmp_lt_i64_e64 s[0:1], s[28:29], v[144:145]
	s_cbranch_vccnz .LBB0_126
	s_ashr_i32 s24, s28, 31
	s_lshr_b32 s24, s24, 29
	s_add_i32 s24, s28, s24
	s_ashr_i32 s25, s24, 3
	s_and_b32 s24, s24, -8
	s_sub_i32 s24, s28, s24
	s_cmp_lt_i32 s24, 0
	s_cselect_b32 s26, s46, 0x140
	s_mul_i32 s24, s24, s26
	s_add_i32 s24, s24, s25
	s_mul_hi_i32 s25, s24, 0x66666667
	s_lshr_b32 s26, s25, 31
	s_ashr_i32 s25, s25, 5
	s_add_i32 s25, s25, s26
	s_lshl_b32 s26, s25, 3
	s_sub_i32 s27, 0x100, s26
	s_min_i32 s27, s27, 8
	s_abs_i32 s28, s27
	v_cvt_f32_u32_e32 v2, s28
	s_sub_i32 s30, 0, s28
	s_mulk_i32 s25, 0x50
	s_sub_i32 s25, s24, s25
	v_rcp_iflag_f32_e32 v2, v2
	s_abs_i32 s24, s25
	s_xor_b32 s29, s25, s27
	s_ashr_i32 s29, s29, 31
	v_mul_f32_e32 v2, 0x4f7ffffe, v2
	v_cvt_u32_f32_e32 v2, v2
	s_nop 0
	v_readfirstlane_b32 s31, v2
	s_mul_i32 s30, s30, s31
	s_mul_hi_u32 s30, s31, s30
	s_add_i32 s31, s31, s30
	s_mul_hi_u32 s30, s24, s31
	s_mul_i32 s31, s30, s28
	s_sub_i32 s24, s24, s31
	s_add_i32 s42, s30, 1
	s_sub_i32 s31, s24, s28
	s_cmp_ge_u32 s24, s28
	s_cselect_b32 s30, s42, s30
	s_cselect_b32 s24, s31, s24
	s_add_i32 s31, s30, 1
	s_cmp_ge_u32 s24, s28
	s_cselect_b32 s24, s31, s30
	s_xor_b32 s24, s24, s29
	s_sub_i32 s24, s24, s29
	s_mul_i32 s27, s24, s27
	s_sub_i32 s25, s25, s27
	s_add_i32 s26, s26, s25

.LBB0_127:
	ds_read_b128 v[154:157], v151
	ds_read_b128 v[158:161], v151 offset:1024
	ds_read_b128 v[162:165], v151 offset:2048
	ds_read_b128 v[166:169], v151 offset:3072
	ds_read_b128 v[170:173], v152
	ds_read_b128 v[174:177], v152 offset:1024
	ds_read_b128 v[178:181], v152 offset:2048
	ds_read_b128 v[182:185], v152 offset:3072
	s_add_u32 s40, s38, 0xfffc0080
	s_addc_u32 s41, s39, -1
	s_cmp_eq_u32 s89, 12
	s_cselect_b32 s43, s27, s41
	s_cselect_b32 s42, s85, s40
	s_cselect_b32 s41, s25, s88
	s_cselect_b32 s40, s86, s87
	v_lshl_add_u64 v[218:219], s[38:39], 0, v[140:141]
	s_add_i32 m0, s47, 0xc000
	ds_read_b128 v[186:189], v153
	ds_read_b128 v[190:193], v153 offset:1024
	ds_read_b128 v[194:197], v153 offset:2048
	ds_read_b128 v[198:201], v153 offset:3072
	ds_read_b128 v[202:205], v153 offset:4096
	ds_read_b128 v[206:209], v153 offset:5120
	ds_read_b128 v[210:213], v153 offset:6144
	ds_read_b128 v[214:217], v153 offset:7168
	global_load_lds_dwordx4 v[218:219], off
	v_lshl_add_u64 v[218:219], s[38:39], 0, v[142:143]
	s_add_i32 m0, s47, 0xe000
	s_nop 0
	global_load_lds_dwordx4 v[218:219], off
	s_waitcnt vmcnt(8)
	s_waitcnt lgkmcnt(0)
	s_barrier
	s_setprio 1
	s_waitcnt lgkmcnt(0)
	v_mfma_f32_16x16x32_bf16 v[126:129], v[154:157], v[186:189], v[126:129]
	v_mfma_f32_16x16x32_bf16 v[122:125], v[162:165], v[186:189], v[122:125]
	v_mfma_f32_16x16x32_bf16 v[118:121], v[154:157], v[194:197], v[118:121]
	v_mfma_f32_16x16x32_bf16 v[114:117], v[162:165], v[194:197], v[114:117]
	v_mfma_f32_16x16x32_bf16 v[110:113], v[154:157], v[202:205], v[110:113]
	v_mfma_f32_16x16x32_bf16 v[106:109], v[162:165], v[202:205], v[106:109]
	v_mfma_f32_16x16x32_bf16 v[102:105], v[154:157], v[210:213], v[102:105]
	v_mfma_f32_16x16x32_bf16 v[98:101], v[162:165], v[210:213], v[98:101]
	v_mfma_f32_16x16x32_bf16 v[126:129], v[158:161], v[190:193], v[126:129]
	v_mfma_f32_16x16x32_bf16 v[122:125], v[166:169], v[190:193], v[122:125]
	v_mfma_f32_16x16x32_bf16 v[118:121], v[158:161], v[198:201], v[118:121]
	v_mfma_f32_16x16x32_bf16 v[114:117], v[166:169], v[198:201], v[114:117]
	v_mfma_f32_16x16x32_bf16 v[110:113], v[158:161], v[206:209], v[110:113]
	v_mfma_f32_16x16x32_bf16 v[106:109], v[166:169], v[206:209], v[106:109]
	v_mfma_f32_16x16x32_bf16 v[102:105], v[158:161], v[214:217], v[102:105]
	v_mfma_f32_16x16x32_bf16 v[98:101], v[166:169], v[214:217], v[98:101]
	s_setprio 0
	s_setprio 1
	v_mfma_f32_16x16x32_bf16 v[78:81], v[170:173], v[186:189], v[78:81]
	v_mfma_f32_16x16x32_bf16 v[70:73], v[178:181], v[186:189], v[70:73]
	v_mfma_f32_16x16x32_bf16 v[62:65], v[170:173], v[194:197], v[62:65]
	v_mfma_f32_16x16x32_bf16 v[54:57], v[178:181], v[194:197], v[54:57]
	v_mfma_f32_16x16x32_bf16 v[46:49], v[170:173], v[202:205], v[46:49]
	v_mfma_f32_16x16x32_bf16 v[42:45], v[178:181], v[202:205], v[42:45]
	v_mfma_f32_16x16x32_bf16 v[38:41], v[170:173], v[210:213], v[38:41]
	v_mfma_f32_16x16x32_bf16 v[34:37], v[178:181], v[210:213], v[34:37]
	v_mfma_f32_16x16x32_bf16 v[78:81], v[174:177], v[190:193], v[78:81]
	v_mfma_f32_16x16x32_bf16 v[70:73], v[182:185], v[190:193], v[70:73]
	v_mfma_f32_16x16x32_bf16 v[62:65], v[174:177], v[198:201], v[62:65]
	v_mfma_f32_16x16x32_bf16 v[54:57], v[182:185], v[198:201], v[54:57]
	v_mfma_f32_16x16x32_bf16 v[46:49], v[174:177], v[206:209], v[46:49]
	v_mfma_f32_16x16x32_bf16 v[42:45], v[182:185], v[206:209], v[42:45]
	v_mfma_f32_16x16x32_bf16 v[38:41], v[174:177], v[214:217], v[38:41]
	v_mfma_f32_16x16x32_bf16 v[34:37], v[182:185], v[214:217], v[34:37]
	s_setprio 0
	s_barrier
	s_add_i32 s90, s83, s44
	v_lshl_add_u64 v[218:219], s[40:41], 0, v[134:135]
	s_mov_b32 m0, s90
	ds_read_b128 v[186:189], v153 offset:16384
	ds_read_b128 v[190:193], v153 offset:17408
	ds_read_b128 v[194:197], v153 offset:18432
	ds_read_b128 v[198:201], v153 offset:19456
	ds_read_b128 v[202:205], v153 offset:20480
	ds_read_b128 v[206:209], v153 offset:21504
	ds_read_b128 v[210:213], v153 offset:22528
	ds_read_b128 v[214:217], v153 offset:23552
	global_load_lds_dwordx4 v[218:219], off
	s_add_i32 m0, s90, 0x2000
	s_add_u32 s90, s40, 0x40000
	v_lshl_add_u64 v[220:221], s[40:41], 0, v[130:131]
	s_addc_u32 s91, s41, 0
	s_add_i32 s92, s84, s44
	global_load_lds_dwordx4 v[220:221], off
	v_lshl_add_u64 v[222:223], s[90:91], 0, v[134:135]
	s_mov_b32 m0, s92
	v_lshl_add_u64 v[224:225], s[42:43], 0, v[132:133]
	global_load_lds_dwordx4 v[222:223], off
	v_lshl_add_u64 v[222:223], s[90:91], 0, v[130:131]
	s_add_i32 m0, s92, 0x2000
	s_nop 0
	global_load_lds_dwordx4 v[222:223], off
	v_lshl_add_u64 v[222:223], s[42:43], 0, v[136:137]
	s_mov_b32 m0, s47
	s_nop 0
	global_load_lds_dwordx4 v[222:223], off
	s_mov_b32 m0, s50
	s_nop 0
	global_load_lds_dwordx4 v[224:225], off
	s_cmp_lg_u32 s33, 0
	s_cbranch_scc1 .Lp1d_nopub
	v_readfirstlane_b32 s96, v252
	s_nop 3
	v_mov_b32_e32 v251, s96
	ds_write_b32 v255, v251
.Lp1d_nopub:
	s_waitcnt vmcnt(8)
	s_waitcnt lgkmcnt(0)
	s_barrier
	s_setprio 1
	s_waitcnt lgkmcnt(0)
	v_mfma_f32_16x16x32_bf16 v[94:97], v[154:157], v[186:189], v[94:97]
	v_mfma_f32_16x16x32_bf16 v[90:93], v[162:165], v[186:189], v[90:93]
	v_mfma_f32_16x16x32_bf16 v[86:89], v[154:157], v[194:197], v[86:89]
	v_mfma_f32_16x16x32_bf16 v[82:85], v[162:165], v[194:197], v[82:85]
	v_mfma_f32_16x16x32_bf16 v[74:77], v[154:157], v[202:205], v[74:77]
	v_mfma_f32_16x16x32_bf16 v[66:69], v[162:165], v[202:205], v[66:69]
	v_mfma_f32_16x16x32_bf16 v[58:61], v[154:157], v[210:213], v[58:61]
	v_mfma_f32_16x16x32_bf16 v[50:53], v[162:165], v[210:213], v[50:53]
	v_mfma_f32_16x16x32_bf16 v[94:97], v[158:161], v[190:193], v[94:97]
	v_mfma_f32_16x16x32_bf16 v[90:93], v[166:169], v[190:193], v[90:93]
	v_mfma_f32_16x16x32_bf16 v[86:89], v[158:161], v[198:201], v[86:89]
	v_mfma_f32_16x16x32_bf16 v[82:85], v[166:169], v[198:201], v[82:85]
	v_mfma_f32_16x16x32_bf16 v[74:77], v[158:161], v[206:209], v[74:77]
	v_mfma_f32_16x16x32_bf16 v[66:69], v[166:169], v[206:209], v[66:69]
	v_mfma_f32_16x16x32_bf16 v[58:61], v[158:161], v[214:217], v[58:61]
	v_mfma_f32_16x16x32_bf16 v[50:53], v[166:169], v[214:217], v[50:53]
	s_setprio 0
	s_setprio 1
	v_mfma_f32_16x16x32_bf16 v[30:33], v[170:173], v[186:189], v[30:33]
	v_mfma_f32_16x16x32_bf16 v[26:29], v[178:181], v[186:189], v[26:29]
	v_mfma_f32_16x16x32_bf16 v[22:25], v[170:173], v[194:197], v[22:25]
	v_mfma_f32_16x16x32_bf16 v[18:21], v[178:181], v[194:197], v[18:21]
	v_mfma_f32_16x16x32_bf16 v[14:17], v[170:173], v[202:205], v[14:17]
	v_mfma_f32_16x16x32_bf16 v[10:13], v[178:181], v[202:205], v[10:13]
	v_mfma_f32_16x16x32_bf16 v[6:9], v[170:173], v[210:213], v[6:9]
	v_mfma_f32_16x16x32_bf16 v[2:5], v[178:181], v[210:213], v[2:5]
	v_mfma_f32_16x16x32_bf16 v[30:33], v[174:177], v[190:193], v[30:33]
	v_mfma_f32_16x16x32_bf16 v[26:29], v[182:185], v[190:193], v[26:29]
	v_mfma_f32_16x16x32_bf16 v[22:25], v[174:177], v[198:201], v[22:25]
	v_mfma_f32_16x16x32_bf16 v[18:21], v[182:185], v[198:201], v[18:21]
	v_mfma_f32_16x16x32_bf16 v[14:17], v[174:177], v[206:209], v[14:17]
	v_mfma_f32_16x16x32_bf16 v[10:13], v[182:185], v[206:209], v[10:13]
	v_mfma_f32_16x16x32_bf16 v[6:9], v[174:177], v[214:217], v[6:9]
	v_mfma_f32_16x16x32_bf16 v[2:5], v[182:185], v[214:217], v[2:5]
	s_setprio 0
	s_barrier
	s_add_i32 s90, 0, 0x18000
	s_add_i32 s91, 0, 0x1c000
	v_add_u32_e32 v166, s90, v150
	v_add_u32_e32 v182, s91, v150
	ds_read_b128 v[154:157], v166
	ds_read_b128 v[158:161], v166 offset:1024
	ds_read_b128 v[162:165], v166 offset:2048
	ds_read_b128 v[166:169], v166 offset:3072
	ds_read_b128 v[170:173], v182
	ds_read_b128 v[174:177], v182 offset:1024
	ds_read_b128 v[178:181], v182 offset:2048
	ds_read_b128 v[182:185], v182 offset:3072
	s_add_u32 s42, s42, 0x40000
	s_addc_u32 s43, s43, 0
	s_mov_b32 m0, s51
	v_lshl_add_u64 v[226:227], s[42:43], 0, v[136:137]
	ds_read_b128 v[186:189], v153 offset:32768
	ds_read_b128 v[190:193], v153 offset:33792
	ds_read_b128 v[194:197], v153 offset:34816
	ds_read_b128 v[198:201], v153 offset:35840
	ds_read_b128 v[202:205], v153 offset:36864
	ds_read_b128 v[206:209], v153 offset:37888
	ds_read_b128 v[210:213], v153 offset:38912
	ds_read_b128 v[214:217], v153 offset:39936
	global_load_lds_dwordx4 v[226:227], off
	v_lshl_add_u64 v[226:227], s[42:43], 0, v[132:133]
	s_mov_b32 m0, s52
	s_nop 0
	global_load_lds_dwordx4 v[226:227], off
	s_waitcnt vmcnt(8)
	s_waitcnt lgkmcnt(0)
	s_barrier
	s_setprio 1
	s_waitcnt lgkmcnt(0)
	v_mfma_f32_16x16x32_bf16 v[126:129], v[154:157], v[186:189], v[126:129]
	v_mfma_f32_16x16x32_bf16 v[122:125], v[162:165], v[186:189], v[122:125]
	v_mfma_f32_16x16x32_bf16 v[118:121], v[154:157], v[194:197], v[118:121]
	v_mfma_f32_16x16x32_bf16 v[114:117], v[162:165], v[194:197], v[114:117]
	v_mfma_f32_16x16x32_bf16 v[110:113], v[154:157], v[202:205], v[110:113]
	v_mfma_f32_16x16x32_bf16 v[106:109], v[162:165], v[202:205], v[106:109]
	v_mfma_f32_16x16x32_bf16 v[102:105], v[154:157], v[210:213], v[102:105]
	v_mfma_f32_16x16x32_bf16 v[98:101], v[162:165], v[210:213], v[98:101]
	v_mfma_f32_16x16x32_bf16 v[126:129], v[158:161], v[190:193], v[126:129]
	v_mfma_f32_16x16x32_bf16 v[122:125], v[166:169], v[190:193], v[122:125]
	v_mfma_f32_16x16x32_bf16 v[118:121], v[158:161], v[198:201], v[118:121]
	v_mfma_f32_16x16x32_bf16 v[114:117], v[166:169], v[198:201], v[114:117]
	v_mfma_f32_16x16x32_bf16 v[110:113], v[158:161], v[206:209], v[110:113]
	v_mfma_f32_16x16x32_bf16 v[106:109], v[166:169], v[206:209], v[106:109]
	v_mfma_f32_16x16x32_bf16 v[102:105], v[158:161], v[214:217], v[102:105]
	v_mfma_f32_16x16x32_bf16 v[98:101], v[166:169], v[214:217], v[98:101]
	s_setprio 0
	s_setprio 1
	v_mfma_f32_16x16x32_bf16 v[78:81], v[170:173], v[186:189], v[78:81]
	v_mfma_f32_16x16x32_bf16 v[70:73], v[178:181], v[186:189], v[70:73]
	v_mfma_f32_16x16x32_bf16 v[62:65], v[170:173], v[194:197], v[62:65]
	v_mfma_f32_16x16x32_bf16 v[54:57], v[178:181], v[194:197], v[54:57]
	v_mfma_f32_16x16x32_bf16 v[46:49], v[170:173], v[202:205], v[46:49]
	v_mfma_f32_16x16x32_bf16 v[42:45], v[178:181], v[202:205], v[42:45]
	v_mfma_f32_16x16x32_bf16 v[38:41], v[170:173], v[210:213], v[38:41]
	v_mfma_f32_16x16x32_bf16 v[34:37], v[178:181], v[210:213], v[34:37]
	v_mfma_f32_16x16x32_bf16 v[78:81], v[174:177], v[190:193], v[78:81]
	v_mfma_f32_16x16x32_bf16 v[70:73], v[182:185], v[190:193], v[70:73]
	v_mfma_f32_16x16x32_bf16 v[62:65], v[174:177], v[198:201], v[62:65]
	v_mfma_f32_16x16x32_bf16 v[54:57], v[182:185], v[198:201], v[54:57]
	v_mfma_f32_16x16x32_bf16 v[46:49], v[174:177], v[206:209], v[46:49]
	v_mfma_f32_16x16x32_bf16 v[42:45], v[182:185], v[206:209], v[42:45]
	v_mfma_f32_16x16x32_bf16 v[38:41], v[174:177], v[214:217], v[38:41]
	v_mfma_f32_16x16x32_bf16 v[34:37], v[182:185], v[214:217], v[34:37]
	s_setprio 0
	s_barrier
	s_add_i32 s42, s90, s44
	v_lshl_add_u64 v[218:219], v[218:219], 0, s[8:9]
	s_mov_b32 m0, s42
	ds_read_b128 v[186:189], v153 offset:49152
	ds_read_b128 v[190:193], v153 offset:50176
	ds_read_b128 v[194:197], v153 offset:51200
	ds_read_b128 v[198:201], v153 offset:52224
	ds_read_b128 v[202:205], v153 offset:53248
	ds_read_b128 v[206:209], v153 offset:54272
	ds_read_b128 v[210:213], v153 offset:55296
	ds_read_b128 v[214:217], v153 offset:56320
	global_load_lds_dwordx4 v[218:219], off
	s_add_i32 m0, s42, 0x2000
	s_add_u32 s40, s40, 0x40080
	v_lshl_add_u64 v[218:219], v[220:221], 0, s[8:9]
	s_addc_u32 s41, s41, 0
	s_add_i32 s42, s91, s44
	global_load_lds_dwordx4 v[218:219], off
	v_lshl_add_u64 v[218:219], s[40:41], 0, v[134:135]
	s_mov_b32 m0, s42
	s_nop 0
	global_load_lds_dwordx4 v[218:219], off
	v_lshl_add_u64 v[218:219], s[40:41], 0, v[130:131]
	s_add_i32 m0, s42, 0x2000
	s_nop 0
	global_load_lds_dwordx4 v[218:219], off
	v_lshl_add_u64 v[218:219], v[222:223], 0, s[8:9]
	s_mov_b32 m0, s80
	s_nop 0
	global_load_lds_dwordx4 v[218:219], off
	v_lshl_add_u64 v[218:219], v[224:225], 0, s[8:9]
	s_mov_b32 m0, s81
	s_nop 0
	global_load_lds_dwordx4 v[218:219], off
	s_waitcnt vmcnt(8)
	s_waitcnt lgkmcnt(0)
	s_barrier
	s_setprio 1
	s_waitcnt lgkmcnt(0)
	v_mfma_f32_16x16x32_bf16 v[94:97], v[154:157], v[186:189], v[94:97]
	v_mfma_f32_16x16x32_bf16 v[90:93], v[162:165], v[186:189], v[90:93]
	v_mfma_f32_16x16x32_bf16 v[86:89], v[154:157], v[194:197], v[86:89]
	v_mfma_f32_16x16x32_bf16 v[82:85], v[162:165], v[194:197], v[82:85]
	v_mfma_f32_16x16x32_bf16 v[74:77], v[154:157], v[202:205], v[74:77]
	v_mfma_f32_16x16x32_bf16 v[66:69], v[162:165], v[202:205], v[66:69]
	v_mfma_f32_16x16x32_bf16 v[58:61], v[154:157], v[210:213], v[58:61]
	v_mfma_f32_16x16x32_bf16 v[50:53], v[162:165], v[210:213], v[50:53]
	v_mfma_f32_16x16x32_bf16 v[94:97], v[158:161], v[190:193], v[94:97]
	v_mfma_f32_16x16x32_bf16 v[90:93], v[166:169], v[190:193], v[90:93]
	v_mfma_f32_16x16x32_bf16 v[86:89], v[158:161], v[198:201], v[86:89]
	v_mfma_f32_16x16x32_bf16 v[82:85], v[166:169], v[198:201], v[82:85]
	v_mfma_f32_16x16x32_bf16 v[74:77], v[158:161], v[206:209], v[74:77]
	v_mfma_f32_16x16x32_bf16 v[66:69], v[166:169], v[206:209], v[66:69]
	v_mfma_f32_16x16x32_bf16 v[58:61], v[158:161], v[214:217], v[58:61]
	v_mfma_f32_16x16x32_bf16 v[50:53], v[166:169], v[214:217], v[50:53]
	s_setprio 0
	s_setprio 1
	v_mfma_f32_16x16x32_bf16 v[30:33], v[170:173], v[186:189], v[30:33]
	v_mfma_f32_16x16x32_bf16 v[26:29], v[178:181], v[186:189], v[26:29]
	v_mfma_f32_16x16x32_bf16 v[22:25], v[170:173], v[194:197], v[22:25]
	v_mfma_f32_16x16x32_bf16 v[18:21], v[178:181], v[194:197], v[18:21]
	v_mfma_f32_16x16x32_bf16 v[14:17], v[170:173], v[202:205], v[14:17]
	v_mfma_f32_16x16x32_bf16 v[10:13], v[178:181], v[202:205], v[10:13]
	v_mfma_f32_16x16x32_bf16 v[6:9], v[170:173], v[210:213], v[6:9]
	v_mfma_f32_16x16x32_bf16 v[2:5], v[178:181], v[210:213], v[2:5]
	v_mfma_f32_16x16x32_bf16 v[30:33], v[174:177], v[190:193], v[30:33]
	v_mfma_f32_16x16x32_bf16 v[26:29], v[182:185], v[190:193], v[26:29]
	v_mfma_f32_16x16x32_bf16 v[22:25], v[174:177], v[198:201], v[22:25]
	v_mfma_f32_16x16x32_bf16 v[18:21], v[182:185], v[198:201], v[18:21]
	v_mfma_f32_16x16x32_bf16 v[14:17], v[174:177], v[206:209], v[14:17]
	v_mfma_f32_16x16x32_bf16 v[10:13], v[182:185], v[206:209], v[10:13]
	v_mfma_f32_16x16x32_bf16 v[6:9], v[174:177], v[214:217], v[6:9]
	v_mfma_f32_16x16x32_bf16 v[2:5], v[182:185], v[214:217], v[2:5]
	s_setprio 0
	s_barrier
	s_add_i32 s89, s89, 2
	s_add_u32 s38, s38, 0x100
	s_addc_u32 s39, s39, 0
	s_add_u32 s87, s87, 0x100
	s_addc_u32 s88, s88, 0
	s_cmp_gt_u32 s89, 13
	s_cbranch_scc0 .LBB0_127
	s_and_b64 vcc, exec, s[10:11]
	s_cbranch_vccz .LBB0_130
	s_barrier
